# accumulator zeroing per unit: 64 v_mov_b64 instead of 128 v_mov_b32 in all 8 gemm phase instances
# baseline (speedup 1.0000x reference)
; template <class Epi, class Sched, bool ALIGN_EPI = false, bool SP2 = false>
; __device__ __forceinline__ void gemm_phase(PG8_LAS unsigned char* lds, const Gemm g, const Sched& S, const Epi& E, int wave_in) {
;     ...
;     f32x4 acc[2][2][4][2];
; #pragma unroll
;     for (int a = 0; a < 2; ++a)
; #pragma unroll
;         for (int b = 0; b < 2; ++b)
; #pragma unroll
;             for (int m = 0; m < 4; ++m)
; #pragma unroll
;                 for (int n = 0; n < 2; ++n) acc[a][b][m][n] = (f32x4){0.f, 0.f, 0.f, 0.f};
;     ...
;         const bool has_next = S.next(ui + 1, nxt);
;         const char* nA = has_next ? (const char*)g.A + (size_t)(nxt.pm >> g.ash) * g.astride + (size_t)nxt.pm * tstep : cA; const char* nB = has_next ? (const char*)g.Bt + (size_t)(nxt.pm >> g.bsh) * g.bstride + (size_t)nxt.pn * tstep : cB;
;         for (int t = 0; t < nt; t += 2) {
;             const bool last = (t == nt - 2);
;             const char* a1 = cA + (size_t)(t + 1) * kstep;
;             const char* a2 = last ? nA : cA + (size_t)(t + 2) * kstep; const char* b2 = last ? nB : cB + (size_t)(t + 2) * kstep;
;             const char* a3 = a2 + kstep; const char* b3 = b2 + kstep;
.LBB0_253:
	s_ashr_i32 s23, s22, 31
	s_lshl_b64 s[24:25], s[22:23], 19
	s_add_u32 s24, s62, s24
	s_addc_u32 s25, s63, s25
	s_and_b64 s[26:27], s[18:19], exec
	s_cselect_b32 s23, s25, s37
	s_cselect_b32 s29, s24, s36
	s_ashr_i32 s21, s20, 31
	s_lshl_b64 s[26:27], s[20:21], 19
	s_add_u32 s26, s64, s26
	s_addc_u32 s27, s65, s27
	s_and_b64 s[38:39], s[18:19], exec
	s_cselect_b32 s21, s27, s35
	s_cselect_b32 s31, s26, s34
	s_add_u32 s76, s34, 0x100
	s_addc_u32 s77, s35, 0
	s_add_u32 s34, s36, 0x40080
	s_addc_u32 s35, s37, 0
	s_mov_b32 s78, -2
	v_mov_b64_e32 v[0:1], 0
	v_mov_b64_e32 v[2:3], 0
	v_mov_b64_e32 v[4:5], 0
	v_mov_b64_e32 v[6:7], 0
	v_mov_b64_e32 v[8:9], 0
	v_mov_b64_e32 v[10:11], 0
	v_mov_b64_e32 v[12:13], 0
	v_mov_b64_e32 v[14:15], 0
	v_mov_b64_e32 v[16:17], 0
	v_mov_b64_e32 v[18:19], 0
	v_mov_b64_e32 v[20:21], 0
	v_mov_b64_e32 v[22:23], 0
	v_mov_b64_e32 v[24:25], 0
	v_mov_b64_e32 v[26:27], 0
	v_mov_b64_e32 v[28:29], 0
	v_mov_b64_e32 v[30:31], 0
	v_mov_b64_e32 v[32:33], 0
	v_mov_b64_e32 v[34:35], 0
	v_mov_b64_e32 v[36:37], 0
	v_mov_b64_e32 v[38:39], 0
	v_mov_b64_e32 v[40:41], 0
	v_mov_b64_e32 v[42:43], 0
	v_mov_b64_e32 v[44:45], 0
	v_mov_b64_e32 v[46:47], 0
	v_mov_b64_e32 v[48:49], 0
	v_mov_b64_e32 v[50:51], 0
	v_mov_b64_e32 v[52:53], 0
	v_mov_b64_e32 v[54:55], 0
	v_mov_b64_e32 v[56:57], 0
	v_mov_b64_e32 v[58:59], 0
	v_mov_b64_e32 v[60:61], 0
	v_mov_b64_e32 v[62:63], 0
	v_mov_b64_e32 v[64:65], 0
	v_mov_b64_e32 v[66:67], 0
	v_mov_b64_e32 v[68:69], 0
	v_mov_b64_e32 v[70:71], 0
	v_mov_b64_e32 v[72:73], 0
	v_mov_b64_e32 v[74:75], 0
	v_mov_b64_e32 v[76:77], 0
	v_mov_b64_e32 v[78:79], 0
	v_mov_b64_e32 v[80:81], 0
	v_mov_b64_e32 v[82:83], 0
	v_mov_b64_e32 v[84:85], 0
	v_mov_b64_e32 v[86:87], 0
	v_mov_b64_e32 v[88:89], 0
	v_mov_b64_e32 v[90:91], 0
	v_mov_b64_e32 v[92:93], 0
	v_mov_b64_e32 v[94:95], 0
	v_mov_b64_e32 v[96:97], 0
	v_mov_b64_e32 v[98:99], 0
	v_mov_b64_e32 v[100:101], 0
	v_mov_b64_e32 v[102:103], 0
	v_mov_b64_e32 v[104:105], 0
	v_mov_b64_e32 v[106:107], 0
	v_mov_b64_e32 v[108:109], 0
	v_mov_b64_e32 v[110:111], 0
	v_mov_b64_e32 v[112:113], 0
	v_mov_b64_e32 v[114:115], 0
	v_mov_b64_e32 v[116:117], 0
	v_mov_b64_e32 v[118:119], 0
	v_mov_b64_e32 v[120:121], 0
	v_mov_b64_e32 v[122:123], 0
	v_mov_b64_e32 v[124:125], 0
	v_mov_b64_e32 v[126:127], 0

; template <class Epi, class Sched, bool ALIGN_EPI = false, bool SP2 = false>
; __device__ __forceinline__ void gemm_phase(PG8_LAS unsigned char* lds, const Gemm g, const Sched& S, const Epi& E, int wave_in) {
;     ...
;     f32x4 acc[2][2][4][2];
; #pragma unroll
;     for (int a = 0; a < 2; ++a)
; #pragma unroll
;         for (int b = 0; b < 2; ++b)
; #pragma unroll
;             for (int m = 0; m < 4; ++m)
; #pragma unroll
;                 for (int n = 0; n < 2; ++n) acc[a][b][m][n] = (f32x4){0.f, 0.f, 0.f, 0.f};
;     ...
;         const bool has_next = S.next(ui + 1, nxt);
;         const char* nA = has_next ? (const char*)g.A + (size_t)(nxt.pm >> g.ash) * g.astride + (size_t)nxt.pm * tstep : cA; const char* nB = has_next ? (const char*)g.Bt + (size_t)(nxt.pm >> g.bsh) * g.bstride + (size_t)nxt.pn * tstep : cB;
;         for (int t = 0; t < nt; t += 2) {
;             const bool last = (t == nt - 2);
;             const char* a1 = cA + (size_t)(t + 1) * kstep;
;             const char* a2 = last ? nA : cA + (size_t)(t + 2) * kstep; const char* b2 = last ? nB : cB + (size_t)(t + 2) * kstep;
;             const char* a3 = a2 + kstep; const char* b3 = b2 + kstep;
.LBB0_272:
	s_ashr_i32 s77, s76, 31
	s_lshl_b64 s[8:9], s[76:77], 19
	s_add_u32 s84, s22, s8
	s_addc_u32 s85, s23, s9
	s_and_b64 s[8:9], s[40:41], exec
	s_cselect_b32 s8, s85, s5
	s_cselect_b32 s9, s84, s4
	s_ashr_i32 s95, s94, 31
	s_lshl_b64 s[10:11], s[94:95], 19
	v_readlane_b32 s16, v255, 39
	v_readlane_b32 s17, v255, 40
	s_add_u32 s24, s16, s10
	s_addc_u32 s25, s17, s11
	s_and_b64 s[10:11], s[40:41], exec
	s_cselect_b32 s16, s25, s1
	s_cselect_b32 s17, s24, s0
	s_add_u32 s31, s0, 0x100
	s_addc_u32 s33, s1, 0
	s_add_u32 s0, s4, 0x40080
	s_addc_u32 s1, s5, 0
	s_mov_b32 s34, -2
	s_waitcnt lgkmcnt(0)
	v_mov_b64_e32 v[0:1], 0
	v_mov_b64_e32 v[2:3], 0
	v_mov_b64_e32 v[4:5], 0
	v_mov_b64_e32 v[6:7], 0
	v_mov_b64_e32 v[8:9], 0
	v_mov_b64_e32 v[10:11], 0
	v_mov_b64_e32 v[12:13], 0
	v_mov_b64_e32 v[14:15], 0
	v_mov_b64_e32 v[16:17], 0
	v_mov_b64_e32 v[18:19], 0
	v_mov_b64_e32 v[20:21], 0
	v_mov_b64_e32 v[22:23], 0
	v_mov_b64_e32 v[24:25], 0
	v_mov_b64_e32 v[26:27], 0
	v_mov_b64_e32 v[28:29], 0
	v_mov_b64_e32 v[30:31], 0
	v_mov_b64_e32 v[32:33], 0
	v_mov_b64_e32 v[34:35], 0
	v_mov_b64_e32 v[36:37], 0
	v_mov_b64_e32 v[38:39], 0
	v_mov_b64_e32 v[40:41], 0
	v_mov_b64_e32 v[42:43], 0
	v_mov_b64_e32 v[44:45], 0
	v_mov_b64_e32 v[46:47], 0
	v_mov_b64_e32 v[48:49], 0
	v_mov_b64_e32 v[50:51], 0
	v_mov_b64_e32 v[52:53], 0
	v_mov_b64_e32 v[54:55], 0
	v_mov_b64_e32 v[56:57], 0
	v_mov_b64_e32 v[58:59], 0
	v_mov_b64_e32 v[60:61], 0
	v_mov_b64_e32 v[62:63], 0
	v_mov_b64_e32 v[64:65], 0
	v_mov_b64_e32 v[66:67], 0
	v_mov_b64_e32 v[68:69], 0
	v_mov_b64_e32 v[70:71], 0
	v_mov_b64_e32 v[72:73], 0
	v_mov_b64_e32 v[74:75], 0
	v_mov_b64_e32 v[76:77], 0
	v_mov_b64_e32 v[78:79], 0
	v_mov_b64_e32 v[80:81], 0
	v_mov_b64_e32 v[82:83], 0
	v_mov_b64_e32 v[84:85], 0
	v_mov_b64_e32 v[86:87], 0
	v_mov_b64_e32 v[88:89], 0
	v_mov_b64_e32 v[90:91], 0
	v_mov_b64_e32 v[92:93], 0
	v_mov_b64_e32 v[94:95], 0
	v_mov_b64_e32 v[96:97], 0
	v_mov_b64_e32 v[98:99], 0
	v_mov_b64_e32 v[100:101], 0
	v_mov_b64_e32 v[102:103], 0
	v_mov_b64_e32 v[104:105], 0
	v_mov_b64_e32 v[106:107], 0
	v_mov_b64_e32 v[108:109], 0
	v_mov_b64_e32 v[110:111], 0
	v_mov_b64_e32 v[112:113], 0
	v_mov_b64_e32 v[114:115], 0
	v_mov_b64_e32 v[116:117], 0
	v_mov_b64_e32 v[118:119], 0
	v_mov_b64_e32 v[120:121], 0
	v_mov_b64_e32 v[122:123], 0
	v_mov_b64_e32 v[124:125], 0
	v_mov_b64_e32 v[126:127], 0

; template <class Epi, class Sched, bool ALIGN_EPI = false, bool SP2 = false>
; __device__ __forceinline__ void gemm_phase(PG8_LAS unsigned char* lds, const Gemm g, const Sched& S, const Epi& E, int wave_in) {
;     ...
;     f32x4 acc[2][2][4][2];
; #pragma unroll
;     for (int a = 0; a < 2; ++a)
; #pragma unroll
;         for (int b = 0; b < 2; ++b)
; #pragma unroll
;             for (int m = 0; m < 4; ++m)
; #pragma unroll
;                 for (int n = 0; n < 2; ++n) acc[a][b][m][n] = (f32x4){0.f, 0.f, 0.f, 0.f};
;     ...
;         const bool has_next = S.next(ui + 1, nxt);
;         const char* nA = has_next ? (const char*)g.A + (size_t)(nxt.pm >> g.ash) * g.astride + (size_t)nxt.pm * tstep : cA; const char* nB = has_next ? (const char*)g.Bt + (size_t)(nxt.pm >> g.bsh) * g.bstride + (size_t)nxt.pn * tstep : cB;
;         for (int t = 0; t < nt; t += 2) {
;             const bool last = (t == nt - 2);
;             const char* a1 = cA + (size_t)(t + 1) * kstep;
;             const char* a2 = last ? nA : cA + (size_t)(t + 2) * kstep; const char* b2 = last ? nB : cB + (size_t)(t + 2) * kstep;
;             const char* a3 = a2 + kstep; const char* b3 = b2 + kstep;
.LBB0_484:
	s_ashr_i32 s15, s14, 31
	s_lshl_b64 s[16:17], s[14:15], 17
	s_add_u32 s16, s47, s16
	s_addc_u32 s17, s46, s17
	s_and_b64 s[18:19], s[10:11], exec
	s_cselect_b32 s15, s17, s25
	s_cselect_b32 s21, s16, s24
	s_ashr_i32 s13, s12, 31
	s_lshl_b64 s[18:19], s[12:13], 17
	s_add_u32 s18, s63, s18
	s_addc_u32 s19, s62, s19
	s_and_b64 s[38:39], s[10:11], exec
	s_cselect_b32 s13, s19, s23
	s_cselect_b32 s27, s18, s22
	s_mov_b32 s34, 0
	s_mov_b64 s[38:39], -1
	s_mov_b64 s[40:41], 0
	v_mov_b64_e32 v[0:1], 0
	v_mov_b64_e32 v[2:3], 0
	v_mov_b64_e32 v[4:5], 0
	v_mov_b64_e32 v[6:7], 0
	v_mov_b64_e32 v[8:9], 0
	v_mov_b64_e32 v[10:11], 0
	v_mov_b64_e32 v[12:13], 0
	v_mov_b64_e32 v[14:15], 0
	v_mov_b64_e32 v[16:17], 0
	v_mov_b64_e32 v[18:19], 0
	v_mov_b64_e32 v[20:21], 0
	v_mov_b64_e32 v[22:23], 0
	v_mov_b64_e32 v[24:25], 0
	v_mov_b64_e32 v[26:27], 0
	v_mov_b64_e32 v[28:29], 0
	v_mov_b64_e32 v[30:31], 0
	v_mov_b64_e32 v[32:33], 0
	v_mov_b64_e32 v[34:35], 0
	v_mov_b64_e32 v[36:37], 0
	v_mov_b64_e32 v[38:39], 0
	v_mov_b64_e32 v[40:41], 0
	v_mov_b64_e32 v[42:43], 0
	v_mov_b64_e32 v[44:45], 0
	v_mov_b64_e32 v[46:47], 0
	v_mov_b64_e32 v[48:49], 0
	v_mov_b64_e32 v[50:51], 0
	v_mov_b64_e32 v[52:53], 0
	v_mov_b64_e32 v[54:55], 0
	v_mov_b64_e32 v[56:57], 0
	v_mov_b64_e32 v[58:59], 0
	v_mov_b64_e32 v[60:61], 0
	v_mov_b64_e32 v[62:63], 0
	v_mov_b64_e32 v[64:65], 0
	v_mov_b64_e32 v[66:67], 0
	v_mov_b64_e32 v[68:69], 0
	v_mov_b64_e32 v[70:71], 0
	v_mov_b64_e32 v[72:73], 0
	v_mov_b64_e32 v[74:75], 0
	v_mov_b64_e32 v[76:77], 0
	v_mov_b64_e32 v[78:79], 0
	v_mov_b64_e32 v[80:81], 0
	v_mov_b64_e32 v[82:83], 0
	v_mov_b64_e32 v[84:85], 0
	v_mov_b64_e32 v[86:87], 0
	v_mov_b64_e32 v[88:89], 0
	v_mov_b64_e32 v[90:91], 0
	v_mov_b64_e32 v[92:93], 0
	v_mov_b64_e32 v[94:95], 0
	v_mov_b64_e32 v[96:97], 0
	v_mov_b64_e32 v[98:99], 0
	v_mov_b64_e32 v[100:101], 0
	v_mov_b64_e32 v[102:103], 0
	v_mov_b64_e32 v[104:105], 0
	v_mov_b64_e32 v[106:107], 0
	v_mov_b64_e32 v[108:109], 0
	v_mov_b64_e32 v[110:111], 0
	v_mov_b64_e32 v[112:113], 0
	v_mov_b64_e32 v[114:115], 0
	v_mov_b64_e32 v[116:117], 0
	v_mov_b64_e32 v[118:119], 0
	v_mov_b64_e32 v[120:121], 0
	v_mov_b64_e32 v[122:123], 0
	v_mov_b64_e32 v[124:125], 0
	v_mov_b64_e32 v[126:127], 0

; template <class Epi, class Sched, bool ALIGN_EPI = false, bool SP2 = false>
; __device__ __forceinline__ void gemm_phase(PG8_LAS unsigned char* lds, const Gemm g, const Sched& S, const Epi& E, int wave_in) {
;     ...
;     f32x4 acc[2][2][4][2];
; #pragma unroll
;     for (int a = 0; a < 2; ++a)
; #pragma unroll
;         for (int b = 0; b < 2; ++b)
; #pragma unroll
;             for (int m = 0; m < 4; ++m)
; #pragma unroll
;                 for (int n = 0; n < 2; ++n) acc[a][b][m][n] = (f32x4){0.f, 0.f, 0.f, 0.f};
;     ...
;         const bool has_next = S.next(ui + 1, nxt);
;         const char* nA = has_next ? (const char*)g.A + (size_t)(nxt.pm >> g.ash) * g.astride + (size_t)nxt.pm * tstep : cA; const char* nB = has_next ? (const char*)g.Bt + (size_t)(nxt.pm >> g.bsh) * g.bstride + (size_t)nxt.pn * tstep : cB;
;         for (int t = 0; t < nt; t += 2) {
;             const bool last = (t == nt - 2);
;             const char* a1 = cA + (size_t)(t + 1) * kstep;
;             const char* a2 = last ? nA : cA + (size_t)(t + 2) * kstep; const char* b2 = last ? nB : cB + (size_t)(t + 2) * kstep;
;             const char* a3 = a2 + kstep; const char* b3 = b2 + kstep;
.LBB0_589:
	s_ashr_i32 s15, s14, 31
	s_lshl_b64 s[20:21], s[14:15], 19
	s_add_u32 s20, s31, s20
	s_addc_u32 s21, s33, s21
	s_and_b64 s[26:27], s[44:45], exec
	s_cselect_b32 s15, s21, s23
	s_cselect_b32 s17, s20, s22
	s_add_u32 s34, s22, 0x100
	s_addc_u32 s44, s23, 0
	s_add_u32 s22, s24, 0x40080
	s_addc_u32 s23, s25, 0
	s_mov_b32 s45, -2
	v_mov_b64_e32 v[0:1], 0
	v_mov_b64_e32 v[2:3], 0
	v_mov_b64_e32 v[4:5], 0
	v_mov_b64_e32 v[6:7], 0
	v_mov_b64_e32 v[8:9], 0
	v_mov_b64_e32 v[10:11], 0
	v_mov_b64_e32 v[12:13], 0
	v_mov_b64_e32 v[14:15], 0
	v_mov_b64_e32 v[16:17], 0
	v_mov_b64_e32 v[18:19], 0
	v_mov_b64_e32 v[20:21], 0
	v_mov_b64_e32 v[22:23], 0
	v_mov_b64_e32 v[24:25], 0
	v_mov_b64_e32 v[26:27], 0
	v_mov_b64_e32 v[28:29], 0
	v_mov_b64_e32 v[30:31], 0
	v_mov_b64_e32 v[32:33], 0
	v_mov_b64_e32 v[34:35], 0
	v_mov_b64_e32 v[36:37], 0
	v_mov_b64_e32 v[38:39], 0
	v_mov_b64_e32 v[40:41], 0
	v_mov_b64_e32 v[42:43], 0
	v_mov_b64_e32 v[44:45], 0
	v_mov_b64_e32 v[46:47], 0
	v_mov_b64_e32 v[48:49], 0
	v_mov_b64_e32 v[50:51], 0
	v_mov_b64_e32 v[52:53], 0
	v_mov_b64_e32 v[54:55], 0
	v_mov_b64_e32 v[56:57], 0
	v_mov_b64_e32 v[58:59], 0
	v_mov_b64_e32 v[60:61], 0
	v_mov_b64_e32 v[62:63], 0
	v_mov_b64_e32 v[64:65], 0
	v_mov_b64_e32 v[66:67], 0
	v_mov_b64_e32 v[68:69], 0
	v_mov_b64_e32 v[70:71], 0
	v_mov_b64_e32 v[72:73], 0
	v_mov_b64_e32 v[74:75], 0
	v_mov_b64_e32 v[76:77], 0
	v_mov_b64_e32 v[78:79], 0
	v_mov_b64_e32 v[80:81], 0
	v_mov_b64_e32 v[82:83], 0
	v_mov_b64_e32 v[84:85], 0
	v_mov_b64_e32 v[86:87], 0
	v_mov_b64_e32 v[88:89], 0
	v_mov_b64_e32 v[90:91], 0
	v_mov_b64_e32 v[92:93], 0
	v_mov_b64_e32 v[94:95], 0
	v_mov_b64_e32 v[96:97], 0
	v_mov_b64_e32 v[98:99], 0
	v_mov_b64_e32 v[100:101], 0
	v_mov_b64_e32 v[102:103], 0
	v_mov_b64_e32 v[104:105], 0
	v_mov_b64_e32 v[106:107], 0
	v_mov_b64_e32 v[108:109], 0
	v_mov_b64_e32 v[110:111], 0
	v_mov_b64_e32 v[116:117], 0
	v_mov_b64_e32 v[118:119], 0
	v_mov_b64_e32 v[132:133], 0
	v_mov_b64_e32 v[134:135], 0
	v_mov_b64_e32 v[148:149], 0
	v_mov_b64_e32 v[150:151], 0
	v_mov_b64_e32 v[152:153], 0
	v_mov_b64_e32 v[154:155], 0

; template <class Epi, class Sched, bool ALIGN_EPI = false, bool SP2 = false>
; __device__ __forceinline__ void gemm_phase(PG8_LAS unsigned char* lds, const Gemm g, const Sched& S, const Epi& E, int wave_in) {
;     ...
;     f32x4 acc[2][2][4][2];
; #pragma unroll
;     for (int a = 0; a < 2; ++a)
; #pragma unroll
;         for (int b = 0; b < 2; ++b)
; #pragma unroll
;             for (int m = 0; m < 4; ++m)
; #pragma unroll
;                 for (int n = 0; n < 2; ++n) acc[a][b][m][n] = (f32x4){0.f, 0.f, 0.f, 0.f};
;     ...
;         const bool has_next = S.next(ui + 1, nxt);
;         const char* nA = has_next ? (const char*)g.A + (size_t)(nxt.pm >> g.ash) * g.astride + (size_t)nxt.pm * tstep : cA; const char* nB = has_next ? (const char*)g.Bt + (size_t)(nxt.pm >> g.bsh) * g.bstride + (size_t)nxt.pn * tstep : cB;
;         for (int t = 0; t < nt; t += 2) {
;             const bool last = (t == nt - 2);
;             const char* a1 = cA + (size_t)(t + 1) * kstep;
;             const char* a2 = last ? nA : cA + (size_t)(t + 2) * kstep; const char* b2 = last ? nB : cB + (size_t)(t + 2) * kstep;
;             const char* a3 = a2 + kstep; const char* b3 = b2 + kstep;
.LBB0_686:
	s_ashr_i32 s17, s16, 31
	s_lshl_b64 s[18:19], s[16:17], 19
	s_add_u32 s18, s8, s18
	s_addc_u32 s19, s9, s19
	s_and_b64 s[20:21], s[42:43], exec
	s_cselect_b32 s17, s19, s25
	s_cselect_b32 s69, s18, s24
	s_ashr_i32 s20, s16, 5
	s_ashr_i32 s21, s20, 31
	s_lshl_b64 s[20:21], s[20:21], 21
	s_add_u32 s26, s31, s20
	s_addc_u32 s27, s33, s21
	s_ashr_i32 s13, s12, 31
	s_lshl_b64 s[20:21], s[12:13], 19
	s_add_u32 s20, s26, s20
	s_addc_u32 s21, s27, s21
	s_and_b64 s[26:27], s[42:43], exec
	s_cselect_b32 s13, s21, s23
	s_cselect_b32 s34, s20, s22
	s_add_u32 s53, s22, 0x100
	s_addc_u32 s71, s23, 0
	s_add_u32 s22, s24, 0x40080
	s_addc_u32 s23, s25, 0
	s_mov_b32 s72, -2
	v_mov_b64_e32 v[0:1], 0
	v_mov_b64_e32 v[2:3], 0
	v_mov_b64_e32 v[4:5], 0
	v_mov_b64_e32 v[6:7], 0
	v_mov_b64_e32 v[8:9], 0
	v_mov_b64_e32 v[10:11], 0
	v_mov_b64_e32 v[12:13], 0
	v_mov_b64_e32 v[14:15], 0
	v_mov_b64_e32 v[16:17], 0
	v_mov_b64_e32 v[18:19], 0
	v_mov_b64_e32 v[20:21], 0
	v_mov_b64_e32 v[22:23], 0
	v_mov_b64_e32 v[24:25], 0
	v_mov_b64_e32 v[26:27], 0
	v_mov_b64_e32 v[28:29], 0
	v_mov_b64_e32 v[30:31], 0
	v_mov_b64_e32 v[32:33], 0
	v_mov_b64_e32 v[34:35], 0
	v_mov_b64_e32 v[36:37], 0
	v_mov_b64_e32 v[38:39], 0
	v_mov_b64_e32 v[40:41], 0
	v_mov_b64_e32 v[42:43], 0
	v_mov_b64_e32 v[44:45], 0
	v_mov_b64_e32 v[46:47], 0
	v_mov_b64_e32 v[48:49], 0
	v_mov_b64_e32 v[50:51], 0
	v_mov_b64_e32 v[52:53], 0
	v_mov_b64_e32 v[54:55], 0
	v_mov_b64_e32 v[56:57], 0
	v_mov_b64_e32 v[58:59], 0
	v_mov_b64_e32 v[60:61], 0
	v_mov_b64_e32 v[62:63], 0
	v_mov_b64_e32 v[64:65], 0
	v_mov_b64_e32 v[66:67], 0
	v_mov_b64_e32 v[68:69], 0
	v_mov_b64_e32 v[70:71], 0
	v_mov_b64_e32 v[72:73], 0
	v_mov_b64_e32 v[74:75], 0
	v_mov_b64_e32 v[76:77], 0
	v_mov_b64_e32 v[78:79], 0
	v_mov_b64_e32 v[80:81], 0
	v_mov_b64_e32 v[82:83], 0
	v_mov_b64_e32 v[84:85], 0
	v_mov_b64_e32 v[86:87], 0
	v_mov_b64_e32 v[88:89], 0
	v_mov_b64_e32 v[90:91], 0
	v_mov_b64_e32 v[92:93], 0
	v_mov_b64_e32 v[94:95], 0
	v_mov_b64_e32 v[96:97], 0
	v_mov_b64_e32 v[98:99], 0
	v_mov_b64_e32 v[100:101], 0
	v_mov_b64_e32 v[102:103], 0
	v_mov_b64_e32 v[104:105], 0
	v_mov_b64_e32 v[106:107], 0
	v_mov_b64_e32 v[108:109], 0
	v_mov_b64_e32 v[110:111], 0
	v_mov_b64_e32 v[112:113], 0
	v_mov_b64_e32 v[114:115], 0
	v_mov_b64_e32 v[116:117], 0
	v_mov_b64_e32 v[118:119], 0
	v_mov_b64_e32 v[120:121], 0
	v_mov_b64_e32 v[122:123], 0
	v_mov_b64_e32 v[124:125], 0
	v_mov_b64_e32 v[126:127], 0

; template <class Epi, class Sched, bool ALIGN_EPI = false, bool SP2 = false>
; __device__ __forceinline__ void gemm_phase(PG8_LAS unsigned char* lds, const Gemm g, const Sched& S, const Epi& E, int wave_in) {
;     ...
;     f32x4 acc[2][2][4][2];
; #pragma unroll
;     for (int a = 0; a < 2; ++a)
; #pragma unroll
;         for (int b = 0; b < 2; ++b)
; #pragma unroll
;             for (int m = 0; m < 4; ++m)
; #pragma unroll
;                 for (int n = 0; n < 2; ++n) acc[a][b][m][n] = (f32x4){0.f, 0.f, 0.f, 0.f};
;     ...
;         const bool has_next = S.next(ui + 1, nxt);
;         const char* nA = has_next ? (const char*)g.A + (size_t)(nxt.pm >> g.ash) * g.astride + (size_t)nxt.pm * tstep : cA; const char* nB = has_next ? (const char*)g.Bt + (size_t)(nxt.pm >> g.bsh) * g.bstride + (size_t)nxt.pn * tstep : cB;
;         for (int t = 0; t < nt; t += 2) {
;             const bool last = (t == nt - 2);
;             const char* a1 = cA + (size_t)(t + 1) * kstep;
;             const char* a2 = last ? nA : cA + (size_t)(t + 2) * kstep; const char* b2 = last ? nB : cB + (size_t)(t + 2) * kstep;
;             const char* a3 = a2 + kstep; const char* b3 = b2 + kstep;
.LBB0_803:
	s_add_u32 s15, s22, 0x100
	s_addc_u32 s17, s23, 0
	s_add_u32 s22, s24, 0x40080
	s_addc_u32 s23, s25, 0
	s_mov_b32 s34, -2
	v_mov_b64_e32 v[0:1], 0
	v_mov_b64_e32 v[2:3], 0
	v_mov_b64_e32 v[4:5], 0
	v_mov_b64_e32 v[6:7], 0
	v_mov_b64_e32 v[8:9], 0
	v_mov_b64_e32 v[10:11], 0
	v_mov_b64_e32 v[12:13], 0
	v_mov_b64_e32 v[14:15], 0
	v_mov_b64_e32 v[16:17], 0
	v_mov_b64_e32 v[18:19], 0
	v_mov_b64_e32 v[20:21], 0
	v_mov_b64_e32 v[22:23], 0
	v_mov_b64_e32 v[24:25], 0
	v_mov_b64_e32 v[26:27], 0
	v_mov_b64_e32 v[28:29], 0
	v_mov_b64_e32 v[30:31], 0
	v_mov_b64_e32 v[32:33], 0
	v_mov_b64_e32 v[34:35], 0
	v_mov_b64_e32 v[36:37], 0
	v_mov_b64_e32 v[38:39], 0
	v_mov_b64_e32 v[40:41], 0
	v_mov_b64_e32 v[42:43], 0
	v_mov_b64_e32 v[44:45], 0
	v_mov_b64_e32 v[46:47], 0
	v_mov_b64_e32 v[48:49], 0
	v_mov_b64_e32 v[50:51], 0
	v_mov_b64_e32 v[52:53], 0
	v_mov_b64_e32 v[54:55], 0
	v_mov_b64_e32 v[56:57], 0
	v_mov_b64_e32 v[58:59], 0
	v_mov_b64_e32 v[60:61], 0
	v_mov_b64_e32 v[62:63], 0
	v_mov_b64_e32 v[64:65], 0
	v_mov_b64_e32 v[66:67], 0
	v_mov_b64_e32 v[68:69], 0
	v_mov_b64_e32 v[70:71], 0
	v_mov_b64_e32 v[72:73], 0
	v_mov_b64_e32 v[74:75], 0
	v_mov_b64_e32 v[76:77], 0
	v_mov_b64_e32 v[78:79], 0
	v_mov_b64_e32 v[80:81], 0
	v_mov_b64_e32 v[82:83], 0
	v_mov_b64_e32 v[84:85], 0
	v_mov_b64_e32 v[86:87], 0
	v_mov_b64_e32 v[88:89], 0
	v_mov_b64_e32 v[90:91], 0
	v_mov_b64_e32 v[92:93], 0
	v_mov_b64_e32 v[94:95], 0
	v_mov_b64_e32 v[96:97], 0
	v_mov_b64_e32 v[98:99], 0
	v_mov_b64_e32 v[100:101], 0
	v_mov_b64_e32 v[102:103], 0
	v_mov_b64_e32 v[104:105], 0
	v_mov_b64_e32 v[106:107], 0
	v_mov_b64_e32 v[108:109], 0
	v_mov_b64_e32 v[110:111], 0
	v_mov_b64_e32 v[116:117], 0
	v_mov_b64_e32 v[118:119], 0
	v_mov_b64_e32 v[132:133], 0
	v_mov_b64_e32 v[134:135], 0
	v_mov_b64_e32 v[148:149], 0
	v_mov_b64_e32 v[150:151], 0
	v_mov_b64_e32 v[152:153], 0
	v_mov_b64_e32 v[154:155], 0

; template <class Epi, class Sched, bool ALIGN_EPI = false, bool SP2 = false>
; __device__ __forceinline__ void gemm_phase(PG8_LAS unsigned char* lds, const Gemm g, const Sched& S, const Epi& E, int wave_in) {
;     ...
;     f32x4 acc[2][2][4][2];
; #pragma unroll
;     for (int a = 0; a < 2; ++a)
; #pragma unroll
;         for (int b = 0; b < 2; ++b)
; #pragma unroll
;             for (int m = 0; m < 4; ++m)
; #pragma unroll
;                 for (int n = 0; n < 2; ++n) acc[a][b][m][n] = (f32x4){0.f, 0.f, 0.f, 0.f};
;     ...
;         const bool has_next = S.next(ui + 1, nxt);
;         const char* nA = has_next ? (const char*)g.A + (size_t)(nxt.pm >> g.ash) * g.astride + (size_t)nxt.pm * tstep : cA; const char* nB = has_next ? (const char*)g.Bt + (size_t)(nxt.pm >> g.bsh) * g.bstride + (size_t)nxt.pn * tstep : cB;
;         for (int t = 0; t < nt; t += 2) {
;             const bool last = (t == nt - 2);
;             const char* a1 = cA + (size_t)(t + 1) * kstep;
;             const char* a2 = last ? nA : cA + (size_t)(t + 2) * kstep; const char* b2 = last ? nB : cB + (size_t)(t + 2) * kstep;
;             const char* a3 = a2 + kstep; const char* b3 = b2 + kstep;
.LBB0_896:
	s_ashr_i32 s11, s10, 31
	s_lshl_b64 s[18:19], s[10:11], 19
	s_add_u32 s66, s6, s18
	s_addc_u32 s67, s72, s19
	s_and_b64 s[18:19], s[46:47], exec
	s_cselect_b32 s11, s67, s1
	s_cselect_b32 s34, s66, s0
	s_ashr_i32 s5, s4, 31
	s_lshl_b64 s[18:19], s[4:5], 19
	s_add_u32 s38, s73, s18
	s_addc_u32 s39, s74, s19
	s_and_b64 s[18:19], s[46:47], exec
	s_cselect_b32 s5, s39, s79
	s_cselect_b32 s53, s38, s78
	s_add_u32 s81, s78, 0x100
	s_addc_u32 s18, s79, 0
	s_add_u32 vcc_lo, s0, 0x40080
	s_addc_u32 vcc_hi, s1, 0
	s_mov_b32 s19, -2
	v_mov_b64_e32 v[0:1], 0
	v_mov_b64_e32 v[2:3], 0
	v_mov_b64_e32 v[4:5], 0
	v_mov_b64_e32 v[6:7], 0
	v_mov_b64_e32 v[8:9], 0
	v_mov_b64_e32 v[10:11], 0
	v_mov_b64_e32 v[12:13], 0
	v_mov_b64_e32 v[14:15], 0
	v_mov_b64_e32 v[16:17], 0
	v_mov_b64_e32 v[18:19], 0
	v_mov_b64_e32 v[20:21], 0
	v_mov_b64_e32 v[22:23], 0
	v_mov_b64_e32 v[24:25], 0
	v_mov_b64_e32 v[26:27], 0
	v_mov_b64_e32 v[28:29], 0
	v_mov_b64_e32 v[30:31], 0
	v_mov_b64_e32 v[32:33], 0
	v_mov_b64_e32 v[34:35], 0
	v_mov_b64_e32 v[36:37], 0
	v_mov_b64_e32 v[38:39], 0
	v_mov_b64_e32 v[40:41], 0
	v_mov_b64_e32 v[42:43], 0
	v_mov_b64_e32 v[44:45], 0
	v_mov_b64_e32 v[46:47], 0
	v_mov_b64_e32 v[48:49], 0
	v_mov_b64_e32 v[50:51], 0
	v_mov_b64_e32 v[52:53], 0
	v_mov_b64_e32 v[54:55], 0
	v_mov_b64_e32 v[56:57], 0
	v_mov_b64_e32 v[58:59], 0
	v_mov_b64_e32 v[60:61], 0
	v_mov_b64_e32 v[62:63], 0
	v_mov_b64_e32 v[64:65], 0
	v_mov_b64_e32 v[66:67], 0
	v_mov_b64_e32 v[68:69], 0
	v_mov_b64_e32 v[70:71], 0
	v_mov_b64_e32 v[72:73], 0
	v_mov_b64_e32 v[74:75], 0
	v_mov_b64_e32 v[76:77], 0
	v_mov_b64_e32 v[78:79], 0
	v_mov_b64_e32 v[80:81], 0
	v_mov_b64_e32 v[82:83], 0
	v_mov_b64_e32 v[84:85], 0
	v_mov_b64_e32 v[86:87], 0
	v_mov_b64_e32 v[88:89], 0
	v_mov_b64_e32 v[90:91], 0
	v_mov_b64_e32 v[92:93], 0
	v_mov_b64_e32 v[94:95], 0
	v_mov_b64_e32 v[96:97], 0
	v_mov_b64_e32 v[98:99], 0
	v_mov_b64_e32 v[100:101], 0
	v_mov_b64_e32 v[102:103], 0
	v_mov_b64_e32 v[104:105], 0
	v_mov_b64_e32 v[106:107], 0
	v_mov_b64_e32 v[108:109], 0
	v_mov_b64_e32 v[110:111], 0
	v_mov_b64_e32 v[112:113], 0
	v_mov_b64_e32 v[114:115], 0
	v_mov_b64_e32 v[116:117], 0
	v_mov_b64_e32 v[118:119], 0
	v_mov_b64_e32 v[120:121], 0
	v_mov_b64_e32 v[122:123], 0
	v_mov_b64_e32 v[124:125], 0
	v_mov_b64_e32 v[126:127], 0

; template <class Epi, class Sched, bool ALIGN_EPI = false, bool SP2 = false>
; __device__ __forceinline__ void gemm_phase(PG8_LAS unsigned char* lds, const Gemm g, const Sched& S, const Epi& E, int wave_in) {
;     ...
;     f32x4 acc[2][2][4][2];
; #pragma unroll
;     for (int a = 0; a < 2; ++a)
; #pragma unroll
;         for (int b = 0; b < 2; ++b)
; #pragma unroll
;             for (int m = 0; m < 4; ++m)
; #pragma unroll
;                 for (int n = 0; n < 2; ++n) acc[a][b][m][n] = (f32x4){0.f, 0.f, 0.f, 0.f};
;     ...
;         const bool has_next = S.next(ui + 1, nxt);
;         const char* nA = has_next ? (const char*)g.A + (size_t)(nxt.pm >> g.ash) * g.astride + (size_t)nxt.pm * tstep : cA; const char* nB = has_next ? (const char*)g.Bt + (size_t)(nxt.pm >> g.bsh) * g.bstride + (size_t)nxt.pn * tstep : cB;
;         for (int t = 0; t < nt; t += 2) {
;             const bool last = (t == nt - 2);
;             const char* a1 = cA + (size_t)(t + 1) * kstep;
;             const char* a2 = last ? nA : cA + (size_t)(t + 2) * kstep; const char* b2 = last ? nB : cB + (size_t)(t + 2) * kstep;
;             const char* a3 = a2 + kstep; const char* b3 = b2 + kstep;
.LBB0_1030:
	s_add_u32 s34, s20, 0x100
	s_addc_u32 s42, s21, 0
	s_mov_b32 s43, -2
	v_mov_b64_e32 v[0:1], 0
	v_mov_b64_e32 v[2:3], 0
	v_mov_b64_e32 v[4:5], 0
	v_mov_b64_e32 v[6:7], 0
	v_mov_b64_e32 v[8:9], 0
	v_mov_b64_e32 v[10:11], 0
	v_mov_b64_e32 v[12:13], 0
	v_mov_b64_e32 v[14:15], 0
	v_mov_b64_e32 v[16:17], 0
	v_mov_b64_e32 v[18:19], 0
	v_mov_b64_e32 v[20:21], 0
	v_mov_b64_e32 v[22:23], 0
	v_mov_b64_e32 v[24:25], 0
	v_mov_b64_e32 v[26:27], 0
	v_mov_b64_e32 v[28:29], 0
	v_mov_b64_e32 v[30:31], 0
	v_mov_b64_e32 v[32:33], 0
	v_mov_b64_e32 v[34:35], 0
	v_mov_b64_e32 v[36:37], 0
	v_mov_b64_e32 v[38:39], 0
	v_mov_b64_e32 v[40:41], 0
	v_mov_b64_e32 v[42:43], 0
	v_mov_b64_e32 v[44:45], 0
	v_mov_b64_e32 v[46:47], 0
	v_mov_b64_e32 v[48:49], 0
	v_mov_b64_e32 v[50:51], 0
	v_mov_b64_e32 v[52:53], 0
	v_mov_b64_e32 v[54:55], 0
	v_mov_b64_e32 v[56:57], 0
	v_mov_b64_e32 v[58:59], 0
	v_mov_b64_e32 v[60:61], 0
	v_mov_b64_e32 v[62:63], 0
	v_mov_b64_e32 v[64:65], 0
	v_mov_b64_e32 v[66:67], 0
	v_mov_b64_e32 v[68:69], 0
	v_mov_b64_e32 v[70:71], 0
	v_mov_b64_e32 v[72:73], 0
	v_mov_b64_e32 v[74:75], 0
	v_mov_b64_e32 v[76:77], 0
	v_mov_b64_e32 v[78:79], 0
	v_mov_b64_e32 v[80:81], 0
	v_mov_b64_e32 v[82:83], 0
	v_mov_b64_e32 v[84:85], 0
	v_mov_b64_e32 v[86:87], 0
	v_mov_b64_e32 v[88:89], 0
	v_mov_b64_e32 v[90:91], 0
	v_mov_b64_e32 v[92:93], 0
	v_mov_b64_e32 v[94:95], 0
	v_mov_b64_e32 v[96:97], 0
	v_mov_b64_e32 v[98:99], 0
	v_mov_b64_e32 v[100:101], 0
	v_mov_b64_e32 v[102:103], 0
	v_mov_b64_e32 v[104:105], 0
	v_mov_b64_e32 v[106:107], 0
	v_mov_b64_e32 v[108:109], 0
	v_mov_b64_e32 v[110:111], 0
	v_mov_b64_e32 v[116:117], 0
	v_mov_b64_e32 v[118:119], 0
	v_mov_b64_e32 v[132:133], 0
	v_mov_b64_e32 v[134:135], 0
	v_mov_b64_e32 v[148:149], 0
	v_mov_b64_e32 v[150:151], 0
	v_mov_b64_e32 v[152:153], 0
	v_mov_b64_e32 v[154:155], 0
